# GEMM epilogue de-serialisation: LoRA a-branch epilogue issues 32 operand loads per batch of 16 outputs with one wait (was load/wait/store per element, 192 waits per tile)
# speedup vs baseline: 1.0776x; 1.0170x over previous
.LBB0_497:
	v_lshlrev_b32_e32 v110, 9, v108
	s_andn2_b64 vcc, exec, s[20:21]
	v_ashrrev_i32_e32 v101, 31, v100
	v_add_u32_e32 v102, v100, v110
	v_or_b32_e32 v159, 0x200, v110
	v_or_b32_e32 v158, 0x400, v110
	v_or_b32_e32 v157, 0x600, v110
	v_or_b32_e32 v156, 0x1000, v110
	v_or_b32_e32 v155, 0x1200, v110
	v_or_b32_e32 v154, 0x1400, v110
	v_or_b32_e32 v153, 0x1600, v110
	v_or_b32_e32 v152, 0x2000, v110
	v_or_b32_e32 v151, 0x2200, v110
	v_or_b32_e32 v150, 0x2400, v110
	v_or_b32_e32 v149, 0x2600, v110
	v_or_b32_e32 v148, 0x3000, v110
	v_or_b32_e32 v113, 0x3200, v110
	v_or_b32_e32 v112, 0x3400, v110
	v_or_b32_e32 v111, 0x3600, v110
	s_cbranch_vccnz .LBB0_499
	v_readlane_b32 s4, v252, 52
	v_readlane_b32 s5, v252, 53
	v_readlane_b32 s8, v252, 56
	v_readlane_b32 s9, v252, 57
	v_lshlrev_b64 v[106:107], 2, v[100:101]
	v_lshl_add_u64 v[104:105], s[58:59], 0, v[106:107]
	v_lshl_add_u64 v[106:107], s[0:1], 0, v[106:107]
	global_load_dword v240, v[104:105], off
	global_load_dword v241, v[104:105], off offset:128
	global_load_dword v242, v[106:107], off
	global_load_dword v243, v[106:107], off offset:128
	v_lshlrev_b32_e32 v244, 2, v102
	v_mov_b32_e32 v245, v244
	v_add_u32_e32 v246, 0x1000, v244
	v_add_u32_e32 v247, 0x4000, v244
	v_add_u32_e32 v248, 0x5000, v244
	global_load_dword v204, v245, s[4:5]
	global_load_dword v220, v245, s[8:9]
	global_load_dword v205, v245, s[4:5] offset:128
	global_load_dword v221, v245, s[8:9] offset:128
	global_load_dword v206, v245, s[4:5] offset:2048
	global_load_dword v222, v245, s[8:9] offset:2048
	global_load_dword v207, v245, s[4:5] offset:2176
	global_load_dword v223, v245, s[8:9] offset:2176
	global_load_dword v208, v246, s[4:5]
	global_load_dword v224, v246, s[8:9]
	global_load_dword v209, v246, s[4:5] offset:128
	global_load_dword v225, v246, s[8:9] offset:128
	global_load_dword v210, v246, s[4:5] offset:2048
	global_load_dword v226, v246, s[8:9] offset:2048
	global_load_dword v211, v246, s[4:5] offset:2176
	global_load_dword v227, v246, s[8:9] offset:2176
	global_load_dword v212, v247, s[4:5]
	global_load_dword v228, v247, s[8:9]
	global_load_dword v213, v247, s[4:5] offset:128
	global_load_dword v229, v247, s[8:9] offset:128
	global_load_dword v214, v247, s[4:5] offset:2048
	global_load_dword v230, v247, s[8:9] offset:2048
	global_load_dword v215, v247, s[4:5] offset:2176
	global_load_dword v231, v247, s[8:9] offset:2176
	global_load_dword v216, v248, s[4:5]
	global_load_dword v232, v248, s[8:9]
	global_load_dword v217, v248, s[4:5] offset:128
	global_load_dword v233, v248, s[8:9] offset:128
	global_load_dword v218, v248, s[4:5] offset:2048
	global_load_dword v234, v248, s[8:9] offset:2048
	global_load_dword v219, v248, s[4:5] offset:2176
	global_load_dword v235, v248, s[8:9] offset:2176
	s_waitcnt vmcnt(32)
	v_add_f32_e32 v82, v82, v240
	v_add_f32_e32 v66, v66, v241
	v_add_f32_e32 v83, v83, v240
	v_add_f32_e32 v67, v67, v241
	v_mul_f32_e32 v82, 0xbfb8aa3b, v82
	v_mul_f32_e32 v66, 0xbfb8aa3b, v66
	v_mul_f32_e32 v83, 0xbfb8aa3b, v83
	v_mul_f32_e32 v67, 0xbfb8aa3b, v67
	v_exp_f32_e32 v82, v82
	v_exp_f32_e32 v66, v66
	v_exp_f32_e32 v83, v83
	v_exp_f32_e32 v67, v67
	v_add_f32_e32 v82, 1.0, v82
	v_add_f32_e32 v66, 1.0, v66
	v_add_f32_e32 v83, 1.0, v83
	v_add_f32_e32 v67, 1.0, v67
	v_rcp_f32_e32 v82, v82
	v_rcp_f32_e32 v66, v66
	v_rcp_f32_e32 v83, v83
	v_rcp_f32_e32 v67, v67
	v_add_f32_e32 v84, v84, v240
	v_add_f32_e32 v68, v68, v241
	v_add_f32_e32 v85, v85, v240
	v_add_f32_e32 v69, v69, v241
	v_mul_f32_e32 v84, 0xbfb8aa3b, v84
	v_mul_f32_e32 v68, 0xbfb8aa3b, v68
	v_mul_f32_e32 v85, 0xbfb8aa3b, v85
	v_mul_f32_e32 v69, 0xbfb8aa3b, v69
	v_exp_f32_e32 v84, v84
	v_exp_f32_e32 v68, v68
	v_exp_f32_e32 v85, v85
	v_exp_f32_e32 v69, v69
	v_add_f32_e32 v84, 1.0, v84
	v_add_f32_e32 v68, 1.0, v68
	v_add_f32_e32 v85, 1.0, v85
	v_add_f32_e32 v69, 1.0, v69
	v_rcp_f32_e32 v84, v84
	v_rcp_f32_e32 v68, v68
	v_rcp_f32_e32 v85, v85
	v_rcp_f32_e32 v69, v69
	v_add_f32_e32 v86, v86, v240
	v_add_f32_e32 v70, v70, v241
	v_add_f32_e32 v87, v87, v240
	v_add_f32_e32 v71, v71, v241
	v_mul_f32_e32 v86, 0xbfb8aa3b, v86
	v_mul_f32_e32 v70, 0xbfb8aa3b, v70
	v_mul_f32_e32 v87, 0xbfb8aa3b, v87
	v_mul_f32_e32 v71, 0xbfb8aa3b, v71
	v_exp_f32_e32 v86, v86
	v_exp_f32_e32 v70, v70
	v_exp_f32_e32 v87, v87
	v_exp_f32_e32 v71, v71
	v_add_f32_e32 v86, 1.0, v86
	v_add_f32_e32 v70, 1.0, v70
	v_add_f32_e32 v87, 1.0, v87
	v_add_f32_e32 v71, 1.0, v71
	v_rcp_f32_e32 v86, v86
	v_rcp_f32_e32 v70, v70
	v_rcp_f32_e32 v87, v87
	v_rcp_f32_e32 v71, v71
	v_add_f32_e32 v88, v88, v240
	v_add_f32_e32 v72, v72, v241
	v_add_f32_e32 v89, v89, v240
	v_add_f32_e32 v73, v73, v241
	v_mul_f32_e32 v88, 0xbfb8aa3b, v88
	v_mul_f32_e32 v72, 0xbfb8aa3b, v72
	v_mul_f32_e32 v89, 0xbfb8aa3b, v89
	v_mul_f32_e32 v73, 0xbfb8aa3b, v73
	v_exp_f32_e32 v88, v88
	v_exp_f32_e32 v72, v72
	v_exp_f32_e32 v89, v89
	v_exp_f32_e32 v73, v73
	v_add_f32_e32 v88, 1.0, v88
	v_add_f32_e32 v72, 1.0, v72
	v_add_f32_e32 v89, 1.0, v89
	v_add_f32_e32 v73, 1.0, v73
	v_rcp_f32_e32 v88, v88
	v_rcp_f32_e32 v72, v72
	v_rcp_f32_e32 v89, v89
	v_rcp_f32_e32 v73, v73
	s_waitcnt vmcnt(0)
	v_mul_f32_e32 v204, v82, v204
	v_add_f32_e32 v82, -1.0, v82
	v_mul_f32_e32 v205, v66, v205
	v_add_f32_e32 v66, -1.0, v66
	v_mul_f32_e32 v206, v83, v206
	v_add_f32_e32 v83, -1.0, v83
	v_mul_f32_e32 v207, v67, v207
	v_add_f32_e32 v67, -1.0, v67
	v_mul_f32_e32 v208, v84, v208
	v_add_f32_e32 v84, -1.0, v84
	v_mul_f32_e32 v209, v68, v209
	v_add_f32_e32 v68, -1.0, v68
	v_mul_f32_e32 v210, v85, v210
	v_add_f32_e32 v85, -1.0, v85
	v_mul_f32_e32 v211, v69, v211
	v_add_f32_e32 v69, -1.0, v69
	v_mul_f32_e32 v212, v86, v212
	v_add_f32_e32 v86, -1.0, v86
	v_mul_f32_e32 v213, v70, v213
	v_add_f32_e32 v70, -1.0, v70
	v_mul_f32_e32 v214, v87, v214
	v_add_f32_e32 v87, -1.0, v87
	v_mul_f32_e32 v215, v71, v215
	v_add_f32_e32 v71, -1.0, v71
	v_mul_f32_e32 v216, v88, v216
	v_add_f32_e32 v88, -1.0, v88
	v_mul_f32_e32 v217, v72, v217
	v_add_f32_e32 v72, -1.0, v72
	v_mul_f32_e32 v218, v89, v218
	v_add_f32_e32 v89, -1.0, v89
	v_mul_f32_e32 v219, v73, v219
	v_add_f32_e32 v73, -1.0, v73
	v_fma_f32 v82, v242, v82, 1.0
	v_fma_f32 v66, v243, v66, 1.0
	v_fma_f32 v83, v242, v83, 1.0
	v_fma_f32 v67, v243, v67, 1.0
	v_fma_f32 v84, v242, v84, 1.0
	v_fma_f32 v68, v243, v68, 1.0
	v_fma_f32 v85, v242, v85, 1.0
	v_fma_f32 v69, v243, v69, 1.0
	v_fma_f32 v86, v242, v86, 1.0
	v_fma_f32 v70, v243, v70, 1.0
	v_fma_f32 v87, v242, v87, 1.0
	v_fma_f32 v71, v243, v71, 1.0
	v_fma_f32 v88, v242, v88, 1.0
	v_fma_f32 v72, v243, v72, 1.0
	v_fma_f32 v89, v242, v89, 1.0
	v_fma_f32 v73, v243, v73, 1.0
	v_mul_f32_e32 v220, v82, v220
	v_mul_f32_e32 v221, v66, v221
	v_mul_f32_e32 v222, v83, v222
	v_mul_f32_e32 v223, v67, v223
	v_mul_f32_e32 v224, v84, v224
	v_mul_f32_e32 v225, v68, v225
	v_mul_f32_e32 v226, v85, v226
	v_mul_f32_e32 v227, v69, v227
	v_mul_f32_e32 v228, v86, v228
	v_mul_f32_e32 v229, v70, v229
	v_mul_f32_e32 v230, v87, v230
	v_mul_f32_e32 v231, v71, v231
	v_mul_f32_e32 v232, v88, v232
	v_mul_f32_e32 v233, v72, v233
	v_mul_f32_e32 v234, v89, v234
	v_mul_f32_e32 v235, v73, v235
	global_store_dword v245, v204, s[94:95]
	global_store_dword v245, v220, s[42:43]
	global_store_dword v245, v205, s[94:95] offset:128
	global_store_dword v245, v221, s[42:43] offset:128
	global_store_dword v245, v206, s[94:95] offset:2048
	global_store_dword v245, v222, s[42:43] offset:2048
	global_store_dword v245, v207, s[94:95] offset:2176
	global_store_dword v245, v223, s[42:43] offset:2176
	global_store_dword v246, v208, s[94:95]
	global_store_dword v246, v224, s[42:43]
	global_store_dword v246, v209, s[94:95] offset:128
	global_store_dword v246, v225, s[42:43] offset:128
	global_store_dword v246, v210, s[94:95] offset:2048
	global_store_dword v246, v226, s[42:43] offset:2048
	global_store_dword v246, v211, s[94:95] offset:2176
	global_store_dword v246, v227, s[42:43] offset:2176
	global_store_dword v247, v212, s[94:95]
	global_store_dword v247, v228, s[42:43]
	global_store_dword v247, v213, s[94:95] offset:128
	global_store_dword v247, v229, s[42:43] offset:128
	global_store_dword v247, v214, s[94:95] offset:2048
	global_store_dword v247, v230, s[42:43] offset:2048
	global_store_dword v247, v215, s[94:95] offset:2176
	global_store_dword v247, v231, s[42:43] offset:2176
	global_store_dword v248, v216, s[94:95]
	global_store_dword v248, v232, s[42:43]
	global_store_dword v248, v217, s[94:95] offset:128
	global_store_dword v248, v233, s[42:43] offset:128
	global_store_dword v248, v218, s[94:95] offset:2048
	global_store_dword v248, v234, s[42:43] offset:2048
	global_store_dword v248, v219, s[94:95] offset:2176
	global_store_dword v248, v235, s[42:43] offset:2176
	v_add_u32_e32 v245, 0x8000, v244
	v_add_u32_e32 v246, 0x9000, v244
	v_add_u32_e32 v247, 0xc000, v244
	v_add_u32_e32 v248, 0xd000, v244
	global_load_dword v204, v245, s[4:5]
	global_load_dword v220, v245, s[8:9]
	global_load_dword v205, v245, s[4:5] offset:128
	global_load_dword v221, v245, s[8:9] offset:128
	global_load_dword v206, v245, s[4:5] offset:2048
	global_load_dword v222, v245, s[8:9] offset:2048
	global_load_dword v207, v245, s[4:5] offset:2176
	global_load_dword v223, v245, s[8:9] offset:2176
	global_load_dword v208, v246, s[4:5]
	global_load_dword v224, v246, s[8:9]
	global_load_dword v209, v246, s[4:5] offset:128
	global_load_dword v225, v246, s[8:9] offset:128
	global_load_dword v210, v246, s[4:5] offset:2048
	global_load_dword v226, v246, s[8:9] offset:2048
	global_load_dword v211, v246, s[4:5] offset:2176
	global_load_dword v227, v246, s[8:9] offset:2176
	global_load_dword v212, v247, s[4:5]
	global_load_dword v228, v247, s[8:9]
	global_load_dword v213, v247, s[4:5] offset:128
	global_load_dword v229, v247, s[8:9] offset:128
	global_load_dword v214, v247, s[4:5] offset:2048
	global_load_dword v230, v247, s[8:9] offset:2048
	global_load_dword v215, v247, s[4:5] offset:2176
	global_load_dword v231, v247, s[8:9] offset:2176
	global_load_dword v216, v248, s[4:5]
	global_load_dword v232, v248, s[8:9]
	global_load_dword v217, v248, s[4:5] offset:128
	global_load_dword v233, v248, s[8:9] offset:128
	global_load_dword v218, v248, s[4:5] offset:2048
	global_load_dword v234, v248, s[8:9] offset:2048
	global_load_dword v219, v248, s[4:5] offset:2176
	global_load_dword v235, v248, s[8:9] offset:2176
	v_add_f32_e32 v90, v90, v240
	v_add_f32_e32 v74, v74, v241
	v_add_f32_e32 v91, v91, v240
	v_add_f32_e32 v75, v75, v241
	v_mul_f32_e32 v90, 0xbfb8aa3b, v90
	v_mul_f32_e32 v74, 0xbfb8aa3b, v74
	v_mul_f32_e32 v91, 0xbfb8aa3b, v91
	v_mul_f32_e32 v75, 0xbfb8aa3b, v75
	v_exp_f32_e32 v90, v90
	v_exp_f32_e32 v74, v74
	v_exp_f32_e32 v91, v91
	v_exp_f32_e32 v75, v75
	v_add_f32_e32 v90, 1.0, v90
	v_add_f32_e32 v74, 1.0, v74
	v_add_f32_e32 v91, 1.0, v91
	v_add_f32_e32 v75, 1.0, v75
	v_rcp_f32_e32 v90, v90
	v_rcp_f32_e32 v74, v74
	v_rcp_f32_e32 v91, v91
	v_rcp_f32_e32 v75, v75
	v_add_f32_e32 v92, v92, v240
	v_add_f32_e32 v76, v76, v241
	v_add_f32_e32 v93, v93, v240
	v_add_f32_e32 v77, v77, v241
	v_mul_f32_e32 v92, 0xbfb8aa3b, v92
	v_mul_f32_e32 v76, 0xbfb8aa3b, v76
	v_mul_f32_e32 v93, 0xbfb8aa3b, v93
	v_mul_f32_e32 v77, 0xbfb8aa3b, v77
	v_exp_f32_e32 v92, v92
	v_exp_f32_e32 v76, v76
	v_exp_f32_e32 v93, v93
	v_exp_f32_e32 v77, v77
	v_add_f32_e32 v92, 1.0, v92
	v_add_f32_e32 v76, 1.0, v76
	v_add_f32_e32 v93, 1.0, v93
	v_add_f32_e32 v77, 1.0, v77
	v_rcp_f32_e32 v92, v92
	v_rcp_f32_e32 v76, v76
	v_rcp_f32_e32 v93, v93
	v_rcp_f32_e32 v77, v77
	v_add_f32_e32 v94, v94, v240
	v_add_f32_e32 v78, v78, v241
	v_add_f32_e32 v95, v95, v240
	v_add_f32_e32 v79, v79, v241
	v_mul_f32_e32 v94, 0xbfb8aa3b, v94
	v_mul_f32_e32 v78, 0xbfb8aa3b, v78
	v_mul_f32_e32 v95, 0xbfb8aa3b, v95
	v_mul_f32_e32 v79, 0xbfb8aa3b, v79
	v_exp_f32_e32 v94, v94
	v_exp_f32_e32 v78, v78
	v_exp_f32_e32 v95, v95
	v_exp_f32_e32 v79, v79
	v_add_f32_e32 v94, 1.0, v94
	v_add_f32_e32 v78, 1.0, v78
	v_add_f32_e32 v95, 1.0, v95
	v_add_f32_e32 v79, 1.0, v79
	v_rcp_f32_e32 v94, v94
	v_rcp_f32_e32 v78, v78
	v_rcp_f32_e32 v95, v95
	v_rcp_f32_e32 v79, v79
	v_add_f32_e32 v96, v96, v240
	v_add_f32_e32 v80, v80, v241
	v_add_f32_e32 v97, v97, v240
	v_add_f32_e32 v81, v81, v241
	v_mul_f32_e32 v96, 0xbfb8aa3b, v96
	v_mul_f32_e32 v80, 0xbfb8aa3b, v80
	v_mul_f32_e32 v97, 0xbfb8aa3b, v97
	v_mul_f32_e32 v81, 0xbfb8aa3b, v81
	v_exp_f32_e32 v96, v96
	v_exp_f32_e32 v80, v80
	v_exp_f32_e32 v97, v97
	v_exp_f32_e32 v81, v81
	v_add_f32_e32 v96, 1.0, v96
	v_add_f32_e32 v80, 1.0, v80
	v_add_f32_e32 v97, 1.0, v97
	v_add_f32_e32 v81, 1.0, v81
	v_rcp_f32_e32 v96, v96
	v_rcp_f32_e32 v80, v80
	v_rcp_f32_e32 v97, v97
	v_rcp_f32_e32 v81, v81
	s_waitcnt vmcnt(0)
	v_mul_f32_e32 v204, v90, v204
	v_add_f32_e32 v90, -1.0, v90
	v_mul_f32_e32 v205, v74, v205
	v_add_f32_e32 v74, -1.0, v74
	v_mul_f32_e32 v206, v91, v206
	v_add_f32_e32 v91, -1.0, v91
	v_mul_f32_e32 v207, v75, v207
	v_add_f32_e32 v75, -1.0, v75
	v_mul_f32_e32 v208, v92, v208
	v_add_f32_e32 v92, -1.0, v92
	v_mul_f32_e32 v209, v76, v209
	v_add_f32_e32 v76, -1.0, v76
	v_mul_f32_e32 v210, v93, v210
	v_add_f32_e32 v93, -1.0, v93
	v_mul_f32_e32 v211, v77, v211
	v_add_f32_e32 v77, -1.0, v77
	v_mul_f32_e32 v212, v94, v212
	v_add_f32_e32 v94, -1.0, v94
	v_mul_f32_e32 v213, v78, v213
	v_add_f32_e32 v78, -1.0, v78
	v_mul_f32_e32 v214, v95, v214
	v_add_f32_e32 v95, -1.0, v95
	v_mul_f32_e32 v215, v79, v215
	v_add_f32_e32 v79, -1.0, v79
	v_mul_f32_e32 v216, v96, v216
	v_add_f32_e32 v96, -1.0, v96
	v_mul_f32_e32 v217, v80, v217
	v_add_f32_e32 v80, -1.0, v80
	v_mul_f32_e32 v218, v97, v218
	v_add_f32_e32 v97, -1.0, v97
	v_mul_f32_e32 v219, v81, v219
	v_add_f32_e32 v81, -1.0, v81
	v_fma_f32 v90, v242, v90, 1.0
	v_fma_f32 v74, v243, v74, 1.0
	v_fma_f32 v91, v242, v91, 1.0
	v_fma_f32 v75, v243, v75, 1.0
	v_fma_f32 v92, v242, v92, 1.0
	v_fma_f32 v76, v243, v76, 1.0
	v_fma_f32 v93, v242, v93, 1.0
	v_fma_f32 v77, v243, v77, 1.0
	v_fma_f32 v94, v242, v94, 1.0
	v_fma_f32 v78, v243, v78, 1.0
	v_fma_f32 v95, v242, v95, 1.0
	v_fma_f32 v79, v243, v79, 1.0
	v_fma_f32 v96, v242, v96, 1.0
	v_fma_f32 v80, v243, v80, 1.0
	v_fma_f32 v97, v242, v97, 1.0
	v_fma_f32 v81, v243, v81, 1.0
	v_mul_f32_e32 v220, v90, v220
	v_mul_f32_e32 v221, v74, v221
	v_mul_f32_e32 v222, v91, v222
	v_mul_f32_e32 v223, v75, v223
	v_mul_f32_e32 v224, v92, v224
	v_mul_f32_e32 v225, v76, v225
	v_mul_f32_e32 v226, v93, v226
	v_mul_f32_e32 v227, v77, v227
	v_mul_f32_e32 v228, v94, v228
	v_mul_f32_e32 v229, v78, v229
	v_mul_f32_e32 v230, v95, v230
	v_mul_f32_e32 v231, v79, v231
	v_mul_f32_e32 v232, v96, v232
	v_mul_f32_e32 v233, v80, v233
	v_mul_f32_e32 v234, v97, v234
	v_mul_f32_e32 v235, v81, v235
	global_store_dword v245, v204, s[94:95]
	global_store_dword v245, v220, s[42:43]
	global_store_dword v245, v205, s[94:95] offset:128
	global_store_dword v245, v221, s[42:43] offset:128
	global_store_dword v245, v206, s[94:95] offset:2048
	global_store_dword v245, v222, s[42:43] offset:2048
	global_store_dword v245, v207, s[94:95] offset:2176
	global_store_dword v245, v223, s[42:43] offset:2176
	global_store_dword v246, v208, s[94:95]
	global_store_dword v246, v224, s[42:43]
	global_store_dword v246, v209, s[94:95] offset:128
	global_store_dword v246, v225, s[42:43] offset:128
	global_store_dword v246, v210, s[94:95] offset:2048
	global_store_dword v246, v226, s[42:43] offset:2048
	global_store_dword v246, v211, s[94:95] offset:2176
	global_store_dword v246, v227, s[42:43] offset:2176
	global_store_dword v247, v212, s[94:95]
	global_store_dword v247, v228, s[42:43]
	global_store_dword v247, v213, s[94:95] offset:128
	global_store_dword v247, v229, s[42:43] offset:128
	global_store_dword v247, v214, s[94:95] offset:2048
	global_store_dword v247, v230, s[42:43] offset:2048
	global_store_dword v247, v215, s[94:95] offset:2176
	global_store_dword v247, v231, s[42:43] offset:2176
	global_store_dword v248, v216, s[94:95]
	global_store_dword v248, v232, s[42:43]
	global_store_dword v248, v217, s[94:95] offset:128
	global_store_dword v248, v233, s[42:43] offset:128
	global_store_dword v248, v218, s[94:95] offset:2048
	global_store_dword v248, v234, s[42:43] offset:2048
	global_store_dword v248, v219, s[94:95] offset:2176
	global_store_dword v248, v235, s[42:43] offset:2176
	v_add_u32_e32 v245, 0x10000, v244
	v_add_u32_e32 v246, 0x11000, v244
	v_add_u32_e32 v247, 0x14000, v244
	v_add_u32_e32 v248, 0x15000, v244
	global_load_dword v204, v245, s[4:5]
	global_load_dword v220, v245, s[8:9]
	global_load_dword v205, v245, s[4:5] offset:128
	global_load_dword v221, v245, s[8:9] offset:128
	global_load_dword v206, v245, s[4:5] offset:2048
	global_load_dword v222, v245, s[8:9] offset:2048
	global_load_dword v207, v245, s[4:5] offset:2176
	global_load_dword v223, v245, s[8:9] offset:2176
	global_load_dword v208, v246, s[4:5]
	global_load_dword v224, v246, s[8:9]
	global_load_dword v209, v246, s[4:5] offset:128
	global_load_dword v225, v246, s[8:9] offset:128
	global_load_dword v210, v246, s[4:5] offset:2048
	global_load_dword v226, v246, s[8:9] offset:2048
	global_load_dword v211, v246, s[4:5] offset:2176
	global_load_dword v227, v246, s[8:9] offset:2176
	global_load_dword v212, v247, s[4:5]
	global_load_dword v228, v247, s[8:9]
	global_load_dword v213, v247, s[4:5] offset:128
	global_load_dword v229, v247, s[8:9] offset:128
	global_load_dword v214, v247, s[4:5] offset:2048
	global_load_dword v230, v247, s[8:9] offset:2048
	global_load_dword v215, v247, s[4:5] offset:2176
	global_load_dword v231, v247, s[8:9] offset:2176
	global_load_dword v216, v248, s[4:5]
	global_load_dword v232, v248, s[8:9]
	global_load_dword v217, v248, s[4:5] offset:128
	global_load_dword v233, v248, s[8:9] offset:128
	global_load_dword v218, v248, s[4:5] offset:2048
	global_load_dword v234, v248, s[8:9] offset:2048
	global_load_dword v219, v248, s[4:5] offset:2176
	global_load_dword v235, v248, s[8:9] offset:2176
	v_add_f32_e32 v50, v50, v240
	v_add_f32_e32 v34, v34, v241
	v_add_f32_e32 v51, v51, v240
	v_add_f32_e32 v35, v35, v241
	v_mul_f32_e32 v50, 0xbfb8aa3b, v50
	v_mul_f32_e32 v34, 0xbfb8aa3b, v34
	v_mul_f32_e32 v51, 0xbfb8aa3b, v51
	v_mul_f32_e32 v35, 0xbfb8aa3b, v35
	v_exp_f32_e32 v50, v50
	v_exp_f32_e32 v34, v34
	v_exp_f32_e32 v51, v51
	v_exp_f32_e32 v35, v35
	v_add_f32_e32 v50, 1.0, v50
	v_add_f32_e32 v34, 1.0, v34
	v_add_f32_e32 v51, 1.0, v51
	v_add_f32_e32 v35, 1.0, v35
	v_rcp_f32_e32 v50, v50
	v_rcp_f32_e32 v34, v34
	v_rcp_f32_e32 v51, v51
	v_rcp_f32_e32 v35, v35
	v_add_f32_e32 v52, v52, v240
	v_add_f32_e32 v36, v36, v241
	v_add_f32_e32 v53, v53, v240
	v_add_f32_e32 v37, v37, v241
	v_mul_f32_e32 v52, 0xbfb8aa3b, v52
	v_mul_f32_e32 v36, 0xbfb8aa3b, v36
	v_mul_f32_e32 v53, 0xbfb8aa3b, v53
	v_mul_f32_e32 v37, 0xbfb8aa3b, v37
	v_exp_f32_e32 v52, v52
	v_exp_f32_e32 v36, v36
	v_exp_f32_e32 v53, v53
	v_exp_f32_e32 v37, v37
	v_add_f32_e32 v52, 1.0, v52
	v_add_f32_e32 v36, 1.0, v36
	v_add_f32_e32 v53, 1.0, v53
	v_add_f32_e32 v37, 1.0, v37
	v_rcp_f32_e32 v52, v52
	v_rcp_f32_e32 v36, v36
	v_rcp_f32_e32 v53, v53
	v_rcp_f32_e32 v37, v37
	v_add_f32_e32 v54, v54, v240
	v_add_f32_e32 v38, v38, v241
	v_add_f32_e32 v55, v55, v240
	v_add_f32_e32 v39, v39, v241
	v_mul_f32_e32 v54, 0xbfb8aa3b, v54
	v_mul_f32_e32 v38, 0xbfb8aa3b, v38
	v_mul_f32_e32 v55, 0xbfb8aa3b, v55
	v_mul_f32_e32 v39, 0xbfb8aa3b, v39
	v_exp_f32_e32 v54, v54
	v_exp_f32_e32 v38, v38
	v_exp_f32_e32 v55, v55
	v_exp_f32_e32 v39, v39
	v_add_f32_e32 v54, 1.0, v54
	v_add_f32_e32 v38, 1.0, v38
	v_add_f32_e32 v55, 1.0, v55
	v_add_f32_e32 v39, 1.0, v39
	v_rcp_f32_e32 v54, v54
	v_rcp_f32_e32 v38, v38
	v_rcp_f32_e32 v55, v55
	v_rcp_f32_e32 v39, v39
	v_add_f32_e32 v56, v56, v240
	v_add_f32_e32 v40, v40, v241
	v_add_f32_e32 v57, v57, v240
	v_add_f32_e32 v41, v41, v241
	v_mul_f32_e32 v56, 0xbfb8aa3b, v56
	v_mul_f32_e32 v40, 0xbfb8aa3b, v40
	v_mul_f32_e32 v57, 0xbfb8aa3b, v57
	v_mul_f32_e32 v41, 0xbfb8aa3b, v41
	v_exp_f32_e32 v56, v56
	v_exp_f32_e32 v40, v40
	v_exp_f32_e32 v57, v57
	v_exp_f32_e32 v41, v41
	v_add_f32_e32 v56, 1.0, v56
	v_add_f32_e32 v40, 1.0, v40
	v_add_f32_e32 v57, 1.0, v57
	v_add_f32_e32 v41, 1.0, v41
	v_rcp_f32_e32 v56, v56
	v_rcp_f32_e32 v40, v40
	v_rcp_f32_e32 v57, v57
	v_rcp_f32_e32 v41, v41
	s_waitcnt vmcnt(0)
	v_mul_f32_e32 v204, v50, v204
	v_add_f32_e32 v50, -1.0, v50
	v_mul_f32_e32 v205, v34, v205
	v_add_f32_e32 v34, -1.0, v34
	v_mul_f32_e32 v206, v51, v206
	v_add_f32_e32 v51, -1.0, v51
	v_mul_f32_e32 v207, v35, v207
	v_add_f32_e32 v35, -1.0, v35
	v_mul_f32_e32 v208, v52, v208
	v_add_f32_e32 v52, -1.0, v52
	v_mul_f32_e32 v209, v36, v209
	v_add_f32_e32 v36, -1.0, v36
	v_mul_f32_e32 v210, v53, v210
	v_add_f32_e32 v53, -1.0, v53
	v_mul_f32_e32 v211, v37, v211
	v_add_f32_e32 v37, -1.0, v37
	v_mul_f32_e32 v212, v54, v212
	v_add_f32_e32 v54, -1.0, v54
	v_mul_f32_e32 v213, v38, v213
	v_add_f32_e32 v38, -1.0, v38
	v_mul_f32_e32 v214, v55, v214
	v_add_f32_e32 v55, -1.0, v55
	v_mul_f32_e32 v215, v39, v215
	v_add_f32_e32 v39, -1.0, v39
	v_mul_f32_e32 v216, v56, v216
	v_add_f32_e32 v56, -1.0, v56
	v_mul_f32_e32 v217, v40, v217
	v_add_f32_e32 v40, -1.0, v40
	v_mul_f32_e32 v218, v57, v218
	v_add_f32_e32 v57, -1.0, v57
	v_mul_f32_e32 v219, v41, v219
	v_add_f32_e32 v41, -1.0, v41
	v_fma_f32 v50, v242, v50, 1.0
	v_fma_f32 v34, v243, v34, 1.0
	v_fma_f32 v51, v242, v51, 1.0
	v_fma_f32 v35, v243, v35, 1.0
	v_fma_f32 v52, v242, v52, 1.0
	v_fma_f32 v36, v243, v36, 1.0
	v_fma_f32 v53, v242, v53, 1.0
	v_fma_f32 v37, v243, v37, 1.0
	v_fma_f32 v54, v242, v54, 1.0
	v_fma_f32 v38, v243, v38, 1.0
	v_fma_f32 v55, v242, v55, 1.0
	v_fma_f32 v39, v243, v39, 1.0
	v_fma_f32 v56, v242, v56, 1.0
	v_fma_f32 v40, v243, v40, 1.0
	v_fma_f32 v57, v242, v57, 1.0
	v_fma_f32 v41, v243, v41, 1.0
	v_mul_f32_e32 v220, v50, v220
	v_mul_f32_e32 v221, v34, v221
	v_mul_f32_e32 v222, v51, v222
	v_mul_f32_e32 v223, v35, v223
	v_mul_f32_e32 v224, v52, v224
	v_mul_f32_e32 v225, v36, v225
	v_mul_f32_e32 v226, v53, v226
	v_mul_f32_e32 v227, v37, v227
	v_mul_f32_e32 v228, v54, v228
	v_mul_f32_e32 v229, v38, v229
	v_mul_f32_e32 v230, v55, v230
	v_mul_f32_e32 v231, v39, v231
	v_mul_f32_e32 v232, v56, v232
	v_mul_f32_e32 v233, v40, v233
	v_mul_f32_e32 v234, v57, v234
	v_mul_f32_e32 v235, v41, v235
	global_store_dword v245, v204, s[94:95]
	global_store_dword v245, v220, s[42:43]
	global_store_dword v245, v205, s[94:95] offset:128
	global_store_dword v245, v221, s[42:43] offset:128
	global_store_dword v245, v206, s[94:95] offset:2048
	global_store_dword v245, v222, s[42:43] offset:2048
	global_store_dword v245, v207, s[94:95] offset:2176
	global_store_dword v245, v223, s[42:43] offset:2176
	global_store_dword v246, v208, s[94:95]
	global_store_dword v246, v224, s[42:43]
	global_store_dword v246, v209, s[94:95] offset:128
	global_store_dword v246, v225, s[42:43] offset:128
	global_store_dword v246, v210, s[94:95] offset:2048
	global_store_dword v246, v226, s[42:43] offset:2048
	global_store_dword v246, v211, s[94:95] offset:2176
	global_store_dword v246, v227, s[42:43] offset:2176
	global_store_dword v247, v212, s[94:95]
	global_store_dword v247, v228, s[42:43]
	global_store_dword v247, v213, s[94:95] offset:128
	global_store_dword v247, v229, s[42:43] offset:128
	global_store_dword v247, v214, s[94:95] offset:2048
	global_store_dword v247, v230, s[42:43] offset:2048
	global_store_dword v247, v215, s[94:95] offset:2176
	global_store_dword v247, v231, s[42:43] offset:2176
	global_store_dword v248, v216, s[94:95]
	global_store_dword v248, v232, s[42:43]
	global_store_dword v248, v217, s[94:95] offset:128
	global_store_dword v248, v233, s[42:43] offset:128
	global_store_dword v248, v218, s[94:95] offset:2048
	global_store_dword v248, v234, s[42:43] offset:2048
	global_store_dword v248, v219, s[94:95] offset:2176
	global_store_dword v248, v235, s[42:43] offset:2176
	v_add_u32_e32 v245, 0x18000, v244
	v_add_u32_e32 v246, 0x19000, v244
	v_add_u32_e32 v247, 0x1c000, v244
	v_add_u32_e32 v248, 0x1d000, v244
	global_load_dword v204, v245, s[4:5]
	global_load_dword v220, v245, s[8:9]
	global_load_dword v205, v245, s[4:5] offset:128
	global_load_dword v221, v245, s[8:9] offset:128
	global_load_dword v206, v245, s[4:5] offset:2048
	global_load_dword v222, v245, s[8:9] offset:2048
	global_load_dword v207, v245, s[4:5] offset:2176
	global_load_dword v223, v245, s[8:9] offset:2176
	global_load_dword v208, v246, s[4:5]
	global_load_dword v224, v246, s[8:9]
	global_load_dword v209, v246, s[4:5] offset:128
	global_load_dword v225, v246, s[8:9] offset:128
	global_load_dword v210, v246, s[4:5] offset:2048
	global_load_dword v226, v246, s[8:9] offset:2048
	global_load_dword v211, v246, s[4:5] offset:2176
	global_load_dword v227, v246, s[8:9] offset:2176
	global_load_dword v212, v247, s[4:5]
	global_load_dword v228, v247, s[8:9]
	global_load_dword v213, v247, s[4:5] offset:128
	global_load_dword v229, v247, s[8:9] offset:128
	global_load_dword v214, v247, s[4:5] offset:2048
	global_load_dword v230, v247, s[8:9] offset:2048
	global_load_dword v215, v247, s[4:5] offset:2176
	global_load_dword v231, v247, s[8:9] offset:2176
	global_load_dword v216, v248, s[4:5]
	global_load_dword v232, v248, s[8:9]
	global_load_dword v217, v248, s[4:5] offset:128
	global_load_dword v233, v248, s[8:9] offset:128
	global_load_dword v218, v248, s[4:5] offset:2048
	global_load_dword v234, v248, s[8:9] offset:2048
	global_load_dword v219, v248, s[4:5] offset:2176
	global_load_dword v235, v248, s[8:9] offset:2176
	v_add_f32_e32 v58, v58, v240
	v_add_f32_e32 v42, v42, v241
	v_add_f32_e32 v59, v59, v240
	v_add_f32_e32 v43, v43, v241
	v_mul_f32_e32 v58, 0xbfb8aa3b, v58
	v_mul_f32_e32 v42, 0xbfb8aa3b, v42
	v_mul_f32_e32 v59, 0xbfb8aa3b, v59
	v_mul_f32_e32 v43, 0xbfb8aa3b, v43
	v_exp_f32_e32 v58, v58
	v_exp_f32_e32 v42, v42
	v_exp_f32_e32 v59, v59
	v_exp_f32_e32 v43, v43
	v_add_f32_e32 v58, 1.0, v58
	v_add_f32_e32 v42, 1.0, v42
	v_add_f32_e32 v59, 1.0, v59
	v_add_f32_e32 v43, 1.0, v43
	v_rcp_f32_e32 v58, v58
	v_rcp_f32_e32 v42, v42
	v_rcp_f32_e32 v59, v59
	v_rcp_f32_e32 v43, v43
	v_add_f32_e32 v60, v60, v240
	v_add_f32_e32 v44, v44, v241
	v_add_f32_e32 v61, v61, v240
	v_add_f32_e32 v45, v45, v241
	v_mul_f32_e32 v60, 0xbfb8aa3b, v60
	v_mul_f32_e32 v44, 0xbfb8aa3b, v44
	v_mul_f32_e32 v61, 0xbfb8aa3b, v61
	v_mul_f32_e32 v45, 0xbfb8aa3b, v45
	v_exp_f32_e32 v60, v60
	v_exp_f32_e32 v44, v44
	v_exp_f32_e32 v61, v61
	v_exp_f32_e32 v45, v45
	v_add_f32_e32 v60, 1.0, v60
	v_add_f32_e32 v44, 1.0, v44
	v_add_f32_e32 v61, 1.0, v61
	v_add_f32_e32 v45, 1.0, v45
	v_rcp_f32_e32 v60, v60
	v_rcp_f32_e32 v44, v44
	v_rcp_f32_e32 v61, v61
	v_rcp_f32_e32 v45, v45
	v_add_f32_e32 v62, v62, v240
	v_add_f32_e32 v46, v46, v241
	v_add_f32_e32 v63, v63, v240
	v_add_f32_e32 v47, v47, v241
	v_mul_f32_e32 v62, 0xbfb8aa3b, v62
	v_mul_f32_e32 v46, 0xbfb8aa3b, v46
	v_mul_f32_e32 v63, 0xbfb8aa3b, v63
	v_mul_f32_e32 v47, 0xbfb8aa3b, v47
	v_exp_f32_e32 v62, v62
	v_exp_f32_e32 v46, v46
	v_exp_f32_e32 v63, v63
	v_exp_f32_e32 v47, v47
	v_add_f32_e32 v62, 1.0, v62
	v_add_f32_e32 v46, 1.0, v46
	v_add_f32_e32 v63, 1.0, v63
	v_add_f32_e32 v47, 1.0, v47
	v_rcp_f32_e32 v62, v62
	v_rcp_f32_e32 v46, v46
	v_rcp_f32_e32 v63, v63
	v_rcp_f32_e32 v47, v47
	v_add_f32_e32 v64, v64, v240
	v_add_f32_e32 v48, v48, v241
	v_add_f32_e32 v65, v65, v240
	v_add_f32_e32 v49, v49, v241
	v_mul_f32_e32 v64, 0xbfb8aa3b, v64
	v_mul_f32_e32 v48, 0xbfb8aa3b, v48
	v_mul_f32_e32 v65, 0xbfb8aa3b, v65
	v_mul_f32_e32 v49, 0xbfb8aa3b, v49
	v_exp_f32_e32 v64, v64
	v_exp_f32_e32 v48, v48
	v_exp_f32_e32 v65, v65
	v_exp_f32_e32 v49, v49
	v_add_f32_e32 v64, 1.0, v64
	v_add_f32_e32 v48, 1.0, v48
	v_add_f32_e32 v65, 1.0, v65
	v_add_f32_e32 v49, 1.0, v49
	v_rcp_f32_e32 v64, v64
	v_rcp_f32_e32 v48, v48
	v_rcp_f32_e32 v65, v65
	v_rcp_f32_e32 v49, v49
	s_waitcnt vmcnt(0)
	v_mul_f32_e32 v204, v58, v204
	v_add_f32_e32 v58, -1.0, v58
	v_mul_f32_e32 v205, v42, v205
	v_add_f32_e32 v42, -1.0, v42
	v_mul_f32_e32 v206, v59, v206
	v_add_f32_e32 v59, -1.0, v59
	v_mul_f32_e32 v207, v43, v207
	v_add_f32_e32 v43, -1.0, v43
	v_mul_f32_e32 v208, v60, v208
	v_add_f32_e32 v60, -1.0, v60
	v_mul_f32_e32 v209, v44, v209
	v_add_f32_e32 v44, -1.0, v44
	v_mul_f32_e32 v210, v61, v210
	v_add_f32_e32 v61, -1.0, v61
	v_mul_f32_e32 v211, v45, v211
	v_add_f32_e32 v45, -1.0, v45
	v_mul_f32_e32 v212, v62, v212
	v_add_f32_e32 v62, -1.0, v62
	v_mul_f32_e32 v213, v46, v213
	v_add_f32_e32 v46, -1.0, v46
	v_mul_f32_e32 v214, v63, v214
	v_add_f32_e32 v63, -1.0, v63
	v_mul_f32_e32 v215, v47, v215
	v_add_f32_e32 v47, -1.0, v47
	v_mul_f32_e32 v216, v64, v216
	v_add_f32_e32 v64, -1.0, v64
	v_mul_f32_e32 v217, v48, v217
	v_add_f32_e32 v48, -1.0, v48
	v_mul_f32_e32 v218, v65, v218
	v_add_f32_e32 v65, -1.0, v65
	v_mul_f32_e32 v219, v49, v219
	v_add_f32_e32 v49, -1.0, v49
	v_fma_f32 v58, v242, v58, 1.0
	v_fma_f32 v42, v243, v42, 1.0
	v_fma_f32 v59, v242, v59, 1.0
	v_fma_f32 v43, v243, v43, 1.0
	v_fma_f32 v60, v242, v60, 1.0
	v_fma_f32 v44, v243, v44, 1.0
	v_fma_f32 v61, v242, v61, 1.0
	v_fma_f32 v45, v243, v45, 1.0
	v_fma_f32 v62, v242, v62, 1.0
	v_fma_f32 v46, v243, v46, 1.0
	v_fma_f32 v63, v242, v63, 1.0
	v_fma_f32 v47, v243, v47, 1.0
	v_fma_f32 v64, v242, v64, 1.0
	v_fma_f32 v48, v243, v48, 1.0
	v_fma_f32 v65, v242, v65, 1.0
	v_fma_f32 v49, v243, v49, 1.0
	v_mul_f32_e32 v220, v58, v220
	v_mul_f32_e32 v221, v42, v221
	v_mul_f32_e32 v222, v59, v222
	v_mul_f32_e32 v223, v43, v223
	v_mul_f32_e32 v224, v60, v224
	v_mul_f32_e32 v225, v44, v225
	v_mul_f32_e32 v226, v61, v226
	v_mul_f32_e32 v227, v45, v227
	v_mul_f32_e32 v228, v62, v228
	v_mul_f32_e32 v229, v46, v229
	v_mul_f32_e32 v230, v63, v230
	v_mul_f32_e32 v231, v47, v231
	v_mul_f32_e32 v232, v64, v232
	v_mul_f32_e32 v233, v48, v233
	v_mul_f32_e32 v234, v65, v234
	v_mul_f32_e32 v235, v49, v235
	global_store_dword v245, v204, s[94:95]
	global_store_dword v245, v220, s[42:43]
	global_store_dword v245, v205, s[94:95] offset:128
	global_store_dword v245, v221, s[42:43] offset:128
	global_store_dword v245, v206, s[94:95] offset:2048
	global_store_dword v245, v222, s[42:43] offset:2048
	global_store_dword v245, v207, s[94:95] offset:2176
	global_store_dword v245, v223, s[42:43] offset:2176
	global_store_dword v246, v208, s[94:95]
	global_store_dword v246, v224, s[42:43]
	global_store_dword v246, v209, s[94:95] offset:128
	global_store_dword v246, v225, s[42:43] offset:128
	global_store_dword v246, v210, s[94:95] offset:2048
	global_store_dword v246, v226, s[42:43] offset:2048
	global_store_dword v246, v211, s[94:95] offset:2176
	global_store_dword v246, v227, s[42:43] offset:2176
	global_store_dword v247, v212, s[94:95]
	global_store_dword v247, v228, s[42:43]
	global_store_dword v247, v213, s[94:95] offset:128
	global_store_dword v247, v229, s[42:43] offset:128
	global_store_dword v247, v214, s[94:95] offset:2048
	global_store_dword v247, v230, s[42:43] offset:2048
	global_store_dword v247, v215, s[94:95] offset:2176
	global_store_dword v247, v231, s[42:43] offset:2176
	global_store_dword v248, v216, s[94:95]
	global_store_dword v248, v232, s[42:43]
	global_store_dword v248, v217, s[94:95] offset:128
	global_store_dword v248, v233, s[42:43] offset:128
	global_store_dword v248, v218, s[94:95] offset:2048
	global_store_dword v248, v234, s[42:43] offset:2048
	global_store_dword v248, v219, s[94:95] offset:2176
	global_store_dword v248, v235, s[42:43] offset:2176
	v_add_u32_e32 v245, 0x20000, v244
	v_add_u32_e32 v246, 0x21000, v244
	v_add_u32_e32 v247, 0x24000, v244
	v_add_u32_e32 v248, 0x25000, v244
	global_load_dword v204, v245, s[4:5]
	global_load_dword v220, v245, s[8:9]
	global_load_dword v205, v245, s[4:5] offset:128
	global_load_dword v221, v245, s[8:9] offset:128
	global_load_dword v206, v245, s[4:5] offset:2048
	global_load_dword v222, v245, s[8:9] offset:2048
	global_load_dword v207, v245, s[4:5] offset:2176
	global_load_dword v223, v245, s[8:9] offset:2176
	global_load_dword v208, v246, s[4:5]
	global_load_dword v224, v246, s[8:9]
	global_load_dword v209, v246, s[4:5] offset:128
	global_load_dword v225, v246, s[8:9] offset:128
	global_load_dword v210, v246, s[4:5] offset:2048
	global_load_dword v226, v246, s[8:9] offset:2048
	global_load_dword v211, v246, s[4:5] offset:2176
	global_load_dword v227, v246, s[8:9] offset:2176
	global_load_dword v212, v247, s[4:5]
	global_load_dword v228, v247, s[8:9]
	global_load_dword v213, v247, s[4:5] offset:128
	global_load_dword v229, v247, s[8:9] offset:128
	global_load_dword v214, v247, s[4:5] offset:2048
	global_load_dword v230, v247, s[8:9] offset:2048
	global_load_dword v215, v247, s[4:5] offset:2176
	global_load_dword v231, v247, s[8:9] offset:2176
	global_load_dword v216, v248, s[4:5]
	global_load_dword v232, v248, s[8:9]
	global_load_dword v217, v248, s[4:5] offset:128
	global_load_dword v233, v248, s[8:9] offset:128
	global_load_dword v218, v248, s[4:5] offset:2048
	global_load_dword v234, v248, s[8:9] offset:2048
	global_load_dword v219, v248, s[4:5] offset:2176
	global_load_dword v235, v248, s[8:9] offset:2176
	v_add_f32_e32 v18, v18, v240
	v_add_f32_e32 v2, v2, v241
	v_add_f32_e32 v19, v19, v240
	v_add_f32_e32 v3, v3, v241
	v_mul_f32_e32 v18, 0xbfb8aa3b, v18
	v_mul_f32_e32 v2, 0xbfb8aa3b, v2
	v_mul_f32_e32 v19, 0xbfb8aa3b, v19
	v_mul_f32_e32 v3, 0xbfb8aa3b, v3
	v_exp_f32_e32 v18, v18
	v_exp_f32_e32 v2, v2
	v_exp_f32_e32 v19, v19
	v_exp_f32_e32 v3, v3
	v_add_f32_e32 v18, 1.0, v18
	v_add_f32_e32 v2, 1.0, v2
	v_add_f32_e32 v19, 1.0, v19
	v_add_f32_e32 v3, 1.0, v3
	v_rcp_f32_e32 v18, v18
	v_rcp_f32_e32 v2, v2
	v_rcp_f32_e32 v19, v19
	v_rcp_f32_e32 v3, v3
	v_add_f32_e32 v20, v20, v240
	v_add_f32_e32 v4, v4, v241
	v_add_f32_e32 v21, v21, v240
	v_add_f32_e32 v5, v5, v241
	v_mul_f32_e32 v20, 0xbfb8aa3b, v20
	v_mul_f32_e32 v4, 0xbfb8aa3b, v4
	v_mul_f32_e32 v21, 0xbfb8aa3b, v21
	v_mul_f32_e32 v5, 0xbfb8aa3b, v5
	v_exp_f32_e32 v20, v20
	v_exp_f32_e32 v4, v4
	v_exp_f32_e32 v21, v21
	v_exp_f32_e32 v5, v5
	v_add_f32_e32 v20, 1.0, v20
	v_add_f32_e32 v4, 1.0, v4
	v_add_f32_e32 v21, 1.0, v21
	v_add_f32_e32 v5, 1.0, v5
	v_rcp_f32_e32 v20, v20
	v_rcp_f32_e32 v4, v4
	v_rcp_f32_e32 v21, v21
	v_rcp_f32_e32 v5, v5
	v_add_f32_e32 v22, v22, v240
	v_add_f32_e32 v6, v6, v241
	v_add_f32_e32 v23, v23, v240
	v_add_f32_e32 v7, v7, v241
	v_mul_f32_e32 v22, 0xbfb8aa3b, v22
	v_mul_f32_e32 v6, 0xbfb8aa3b, v6
	v_mul_f32_e32 v23, 0xbfb8aa3b, v23
	v_mul_f32_e32 v7, 0xbfb8aa3b, v7
	v_exp_f32_e32 v22, v22
	v_exp_f32_e32 v6, v6
	v_exp_f32_e32 v23, v23
	v_exp_f32_e32 v7, v7
	v_add_f32_e32 v22, 1.0, v22
	v_add_f32_e32 v6, 1.0, v6
	v_add_f32_e32 v23, 1.0, v23
	v_add_f32_e32 v7, 1.0, v7
	v_rcp_f32_e32 v22, v22
	v_rcp_f32_e32 v6, v6
	v_rcp_f32_e32 v23, v23
	v_rcp_f32_e32 v7, v7
	v_add_f32_e32 v24, v24, v240
	v_add_f32_e32 v8, v8, v241
	v_add_f32_e32 v25, v25, v240
	v_add_f32_e32 v9, v9, v241
	v_mul_f32_e32 v24, 0xbfb8aa3b, v24
	v_mul_f32_e32 v8, 0xbfb8aa3b, v8
	v_mul_f32_e32 v25, 0xbfb8aa3b, v25
	v_mul_f32_e32 v9, 0xbfb8aa3b, v9
	v_exp_f32_e32 v24, v24
	v_exp_f32_e32 v8, v8
	v_exp_f32_e32 v25, v25
	v_exp_f32_e32 v9, v9
	v_add_f32_e32 v24, 1.0, v24
	v_add_f32_e32 v8, 1.0, v8
	v_add_f32_e32 v25, 1.0, v25
	v_add_f32_e32 v9, 1.0, v9
	v_rcp_f32_e32 v24, v24
	v_rcp_f32_e32 v8, v8
	v_rcp_f32_e32 v25, v25
	v_rcp_f32_e32 v9, v9
	s_waitcnt vmcnt(0)
	v_mul_f32_e32 v204, v18, v204
	v_add_f32_e32 v18, -1.0, v18
	v_mul_f32_e32 v205, v2, v205
	v_add_f32_e32 v2, -1.0, v2
	v_mul_f32_e32 v206, v19, v206
	v_add_f32_e32 v19, -1.0, v19
	v_mul_f32_e32 v207, v3, v207
	v_add_f32_e32 v3, -1.0, v3
	v_mul_f32_e32 v208, v20, v208
	v_add_f32_e32 v20, -1.0, v20
	v_mul_f32_e32 v209, v4, v209
	v_add_f32_e32 v4, -1.0, v4
	v_mul_f32_e32 v210, v21, v210
	v_add_f32_e32 v21, -1.0, v21
	v_mul_f32_e32 v211, v5, v211
	v_add_f32_e32 v5, -1.0, v5
	v_mul_f32_e32 v212, v22, v212
	v_add_f32_e32 v22, -1.0, v22
	v_mul_f32_e32 v213, v6, v213
	v_add_f32_e32 v6, -1.0, v6
	v_mul_f32_e32 v214, v23, v214
	v_add_f32_e32 v23, -1.0, v23
	v_mul_f32_e32 v215, v7, v215
	v_add_f32_e32 v7, -1.0, v7
	v_mul_f32_e32 v216, v24, v216
	v_add_f32_e32 v24, -1.0, v24
	v_mul_f32_e32 v217, v8, v217
	v_add_f32_e32 v8, -1.0, v8
	v_mul_f32_e32 v218, v25, v218
	v_add_f32_e32 v25, -1.0, v25
	v_mul_f32_e32 v219, v9, v219
	v_add_f32_e32 v9, -1.0, v9
	v_fma_f32 v18, v242, v18, 1.0
	v_fma_f32 v2, v243, v2, 1.0
	v_fma_f32 v19, v242, v19, 1.0
	v_fma_f32 v3, v243, v3, 1.0
	v_fma_f32 v20, v242, v20, 1.0
	v_fma_f32 v4, v243, v4, 1.0
	v_fma_f32 v21, v242, v21, 1.0
	v_fma_f32 v5, v243, v5, 1.0
	v_fma_f32 v22, v242, v22, 1.0
	v_fma_f32 v6, v243, v6, 1.0
	v_fma_f32 v23, v242, v23, 1.0
	v_fma_f32 v7, v243, v7, 1.0
	v_fma_f32 v24, v242, v24, 1.0
	v_fma_f32 v8, v243, v8, 1.0
	v_fma_f32 v25, v242, v25, 1.0
	v_fma_f32 v9, v243, v9, 1.0
	v_mul_f32_e32 v220, v18, v220
	v_mul_f32_e32 v221, v2, v221
	v_mul_f32_e32 v222, v19, v222
	v_mul_f32_e32 v223, v3, v223
	v_mul_f32_e32 v224, v20, v224
	v_mul_f32_e32 v225, v4, v225
	v_mul_f32_e32 v226, v21, v226
	v_mul_f32_e32 v227, v5, v227
	v_mul_f32_e32 v228, v22, v228
	v_mul_f32_e32 v229, v6, v229
	v_mul_f32_e32 v230, v23, v230
	v_mul_f32_e32 v231, v7, v231
	v_mul_f32_e32 v232, v24, v232
	v_mul_f32_e32 v233, v8, v233
	v_mul_f32_e32 v234, v25, v234
	v_mul_f32_e32 v235, v9, v235
	global_store_dword v245, v204, s[94:95]
	global_store_dword v245, v220, s[42:43]
	global_store_dword v245, v205, s[94:95] offset:128
	global_store_dword v245, v221, s[42:43] offset:128
	global_store_dword v245, v206, s[94:95] offset:2048
	global_store_dword v245, v222, s[42:43] offset:2048
	global_store_dword v245, v207, s[94:95] offset:2176
	global_store_dword v245, v223, s[42:43] offset:2176
	global_store_dword v246, v208, s[94:95]
	global_store_dword v246, v224, s[42:43]
	global_store_dword v246, v209, s[94:95] offset:128
	global_store_dword v246, v225, s[42:43] offset:128
	global_store_dword v246, v210, s[94:95] offset:2048
	global_store_dword v246, v226, s[42:43] offset:2048
	global_store_dword v246, v211, s[94:95] offset:2176
	global_store_dword v246, v227, s[42:43] offset:2176
	global_store_dword v247, v212, s[94:95]
	global_store_dword v247, v228, s[42:43]
	global_store_dword v247, v213, s[94:95] offset:128
	global_store_dword v247, v229, s[42:43] offset:128
	global_store_dword v247, v214, s[94:95] offset:2048
	global_store_dword v247, v230, s[42:43] offset:2048
	global_store_dword v247, v215, s[94:95] offset:2176
	global_store_dword v247, v231, s[42:43] offset:2176
	global_store_dword v248, v216, s[94:95]
	global_store_dword v248, v232, s[42:43]
	global_store_dword v248, v217, s[94:95] offset:128
	global_store_dword v248, v233, s[42:43] offset:128
	global_store_dword v248, v218, s[94:95] offset:2048
	global_store_dword v248, v234, s[42:43] offset:2048
	global_store_dword v248, v219, s[94:95] offset:2176
	global_store_dword v248, v235, s[42:43] offset:2176
	v_add_u32_e32 v245, 0x28000, v244
	v_add_u32_e32 v246, 0x29000, v244
	v_add_u32_e32 v247, 0x2c000, v244
	v_add_u32_e32 v248, 0x2d000, v244
	global_load_dword v204, v245, s[4:5]
	global_load_dword v220, v245, s[8:9]
	global_load_dword v205, v245, s[4:5] offset:128
	global_load_dword v221, v245, s[8:9] offset:128
	global_load_dword v206, v245, s[4:5] offset:2048
	global_load_dword v222, v245, s[8:9] offset:2048
	global_load_dword v207, v245, s[4:5] offset:2176
	global_load_dword v223, v245, s[8:9] offset:2176
	global_load_dword v208, v246, s[4:5]
	global_load_dword v224, v246, s[8:9]
	global_load_dword v209, v246, s[4:5] offset:128
	global_load_dword v225, v246, s[8:9] offset:128
	global_load_dword v210, v246, s[4:5] offset:2048
	global_load_dword v226, v246, s[8:9] offset:2048
	global_load_dword v211, v246, s[4:5] offset:2176
	global_load_dword v227, v246, s[8:9] offset:2176
	global_load_dword v212, v247, s[4:5]
	global_load_dword v228, v247, s[8:9]
	global_load_dword v213, v247, s[4:5] offset:128
	global_load_dword v229, v247, s[8:9] offset:128
	global_load_dword v214, v247, s[4:5] offset:2048
	global_load_dword v230, v247, s[8:9] offset:2048
	global_load_dword v215, v247, s[4:5] offset:2176
	global_load_dword v231, v247, s[8:9] offset:2176
	global_load_dword v216, v248, s[4:5]
	global_load_dword v232, v248, s[8:9]
	global_load_dword v217, v248, s[4:5] offset:128
	global_load_dword v233, v248, s[8:9] offset:128
	global_load_dword v218, v248, s[4:5] offset:2048
	global_load_dword v234, v248, s[8:9] offset:2048
	global_load_dword v219, v248, s[4:5] offset:2176
	global_load_dword v235, v248, s[8:9] offset:2176
	v_add_f32_e32 v26, v26, v240
	v_add_f32_e32 v10, v10, v241
	v_add_f32_e32 v27, v27, v240
	v_add_f32_e32 v11, v11, v241
	v_mul_f32_e32 v26, 0xbfb8aa3b, v26
	v_mul_f32_e32 v10, 0xbfb8aa3b, v10
	v_mul_f32_e32 v27, 0xbfb8aa3b, v27
	v_mul_f32_e32 v11, 0xbfb8aa3b, v11
	v_exp_f32_e32 v26, v26
	v_exp_f32_e32 v10, v10
	v_exp_f32_e32 v27, v27
	v_exp_f32_e32 v11, v11
	v_add_f32_e32 v26, 1.0, v26
	v_add_f32_e32 v10, 1.0, v10
	v_add_f32_e32 v27, 1.0, v27
	v_add_f32_e32 v11, 1.0, v11
	v_rcp_f32_e32 v26, v26
	v_rcp_f32_e32 v10, v10
	v_rcp_f32_e32 v27, v27
	v_rcp_f32_e32 v11, v11
	v_add_f32_e32 v28, v28, v240
	v_add_f32_e32 v12, v12, v241
	v_add_f32_e32 v29, v29, v240
	v_add_f32_e32 v13, v13, v241
	v_mul_f32_e32 v28, 0xbfb8aa3b, v28
	v_mul_f32_e32 v12, 0xbfb8aa3b, v12
	v_mul_f32_e32 v29, 0xbfb8aa3b, v29
	v_mul_f32_e32 v13, 0xbfb8aa3b, v13
	v_exp_f32_e32 v28, v28
	v_exp_f32_e32 v12, v12
	v_exp_f32_e32 v29, v29
	v_exp_f32_e32 v13, v13
	v_add_f32_e32 v28, 1.0, v28
	v_add_f32_e32 v12, 1.0, v12
	v_add_f32_e32 v29, 1.0, v29
	v_add_f32_e32 v13, 1.0, v13
	v_rcp_f32_e32 v28, v28
	v_rcp_f32_e32 v12, v12
	v_rcp_f32_e32 v29, v29
	v_rcp_f32_e32 v13, v13
	v_add_f32_e32 v30, v30, v240
	v_add_f32_e32 v14, v14, v241
	v_add_f32_e32 v31, v31, v240
	v_add_f32_e32 v15, v15, v241
	v_mul_f32_e32 v30, 0xbfb8aa3b, v30
	v_mul_f32_e32 v14, 0xbfb8aa3b, v14
	v_mul_f32_e32 v31, 0xbfb8aa3b, v31
	v_mul_f32_e32 v15, 0xbfb8aa3b, v15
	v_exp_f32_e32 v30, v30
	v_exp_f32_e32 v14, v14
	v_exp_f32_e32 v31, v31
	v_exp_f32_e32 v15, v15
	v_add_f32_e32 v30, 1.0, v30
	v_add_f32_e32 v14, 1.0, v14
	v_add_f32_e32 v31, 1.0, v31
	v_add_f32_e32 v15, 1.0, v15
	v_rcp_f32_e32 v30, v30
	v_rcp_f32_e32 v14, v14
	v_rcp_f32_e32 v31, v31
	v_rcp_f32_e32 v15, v15
	v_add_f32_e32 v32, v32, v240
	v_add_f32_e32 v16, v16, v241
	v_add_f32_e32 v33, v33, v240
	v_add_f32_e32 v17, v17, v241
	v_mul_f32_e32 v32, 0xbfb8aa3b, v32
	v_mul_f32_e32 v16, 0xbfb8aa3b, v16
	v_mul_f32_e32 v33, 0xbfb8aa3b, v33
	v_mul_f32_e32 v17, 0xbfb8aa3b, v17
	v_exp_f32_e32 v32, v32
	v_exp_f32_e32 v16, v16
	v_exp_f32_e32 v33, v33
	v_exp_f32_e32 v17, v17
	v_add_f32_e32 v32, 1.0, v32
	v_add_f32_e32 v16, 1.0, v16
	v_add_f32_e32 v33, 1.0, v33
	v_add_f32_e32 v17, 1.0, v17
	v_rcp_f32_e32 v32, v32
	v_rcp_f32_e32 v16, v16
	v_rcp_f32_e32 v33, v33
	v_rcp_f32_e32 v17, v17
	s_waitcnt vmcnt(0)
	v_mul_f32_e32 v204, v26, v204
	v_add_f32_e32 v26, -1.0, v26
	v_mul_f32_e32 v205, v10, v205
	v_add_f32_e32 v10, -1.0, v10
	v_mul_f32_e32 v206, v27, v206
	v_add_f32_e32 v27, -1.0, v27
	v_mul_f32_e32 v207, v11, v207
	v_add_f32_e32 v11, -1.0, v11
	v_mul_f32_e32 v208, v28, v208
	v_add_f32_e32 v28, -1.0, v28
	v_mul_f32_e32 v209, v12, v209
	v_add_f32_e32 v12, -1.0, v12
	v_mul_f32_e32 v210, v29, v210
	v_add_f32_e32 v29, -1.0, v29
	v_mul_f32_e32 v211, v13, v211
	v_add_f32_e32 v13, -1.0, v13
	v_mul_f32_e32 v212, v30, v212
	v_add_f32_e32 v30, -1.0, v30
	v_mul_f32_e32 v213, v14, v213
	v_add_f32_e32 v14, -1.0, v14
	v_mul_f32_e32 v214, v31, v214
	v_add_f32_e32 v31, -1.0, v31
	v_mul_f32_e32 v215, v15, v215
	v_add_f32_e32 v15, -1.0, v15
	v_mul_f32_e32 v216, v32, v216
	v_add_f32_e32 v32, -1.0, v32
	v_mul_f32_e32 v217, v16, v217
	v_add_f32_e32 v16, -1.0, v16
	v_mul_f32_e32 v218, v33, v218
	v_add_f32_e32 v33, -1.0, v33
	v_mul_f32_e32 v219, v17, v219
	v_add_f32_e32 v17, -1.0, v17
	v_fma_f32 v26, v242, v26, 1.0
	v_fma_f32 v10, v243, v10, 1.0
	v_fma_f32 v27, v242, v27, 1.0
	v_fma_f32 v11, v243, v11, 1.0
	v_fma_f32 v28, v242, v28, 1.0
	v_fma_f32 v12, v243, v12, 1.0
	v_fma_f32 v29, v242, v29, 1.0
	v_fma_f32 v13, v243, v13, 1.0
	v_fma_f32 v30, v242, v30, 1.0
	v_fma_f32 v14, v243, v14, 1.0
	v_fma_f32 v31, v242, v31, 1.0
	v_fma_f32 v15, v243, v15, 1.0
	v_fma_f32 v32, v242, v32, 1.0
	v_fma_f32 v16, v243, v16, 1.0
	v_fma_f32 v33, v242, v33, 1.0
	v_fma_f32 v17, v243, v17, 1.0
	v_mul_f32_e32 v220, v26, v220
	v_mul_f32_e32 v221, v10, v221
	v_mul_f32_e32 v222, v27, v222
	v_mul_f32_e32 v223, v11, v223
	v_mul_f32_e32 v224, v28, v224
	v_mul_f32_e32 v225, v12, v225
	v_mul_f32_e32 v226, v29, v226
	v_mul_f32_e32 v227, v13, v227
	v_mul_f32_e32 v228, v30, v228
	v_mul_f32_e32 v229, v14, v229
	v_mul_f32_e32 v230, v31, v230
	v_mul_f32_e32 v231, v15, v231
	v_mul_f32_e32 v232, v32, v232
	v_mul_f32_e32 v233, v16, v233
	v_mul_f32_e32 v234, v33, v234
	v_mul_f32_e32 v235, v17, v235
	global_store_dword v245, v204, s[94:95]
	global_store_dword v245, v220, s[42:43]
	global_store_dword v245, v205, s[94:95] offset:128
	global_store_dword v245, v221, s[42:43] offset:128
	global_store_dword v245, v206, s[94:95] offset:2048
	global_store_dword v245, v222, s[42:43] offset:2048
	global_store_dword v245, v207, s[94:95] offset:2176
	global_store_dword v245, v223, s[42:43] offset:2176
	global_store_dword v246, v208, s[94:95]
	global_store_dword v246, v224, s[42:43]
	global_store_dword v246, v209, s[94:95] offset:128
	global_store_dword v246, v225, s[42:43] offset:128
	global_store_dword v246, v210, s[94:95] offset:2048
	global_store_dword v246, v226, s[42:43] offset:2048
	global_store_dword v246, v211, s[94:95] offset:2176
	global_store_dword v246, v227, s[42:43] offset:2176
	global_store_dword v247, v212, s[94:95]
	global_store_dword v247, v228, s[42:43]
	global_store_dword v247, v213, s[94:95] offset:128
	global_store_dword v247, v229, s[42:43] offset:128
	global_store_dword v247, v214, s[94:95] offset:2048
	global_store_dword v247, v230, s[42:43] offset:2048
	global_store_dword v247, v215, s[94:95] offset:2176
	global_store_dword v247, v231, s[42:43] offset:2176
	global_store_dword v248, v216, s[94:95]
	global_store_dword v248, v232, s[42:43]
	global_store_dword v248, v217, s[94:95] offset:128
	global_store_dword v248, v233, s[42:43] offset:128
	global_store_dword v248, v218, s[94:95] offset:2048
	global_store_dword v248, v234, s[42:43] offset:2048
	global_store_dword v248, v219, s[94:95] offset:2176
	global_store_dword v248, v235, s[42:43] offset:2176
	s_mov_b64 s[2:3], 0
